# scan: sample-class workgroups throttled with one s_sleep 127 per chunk step (they idle ~110 us anyway) to cut memory contention for the prompt-class critical path
# baseline (speedup 1.0000x reference)
; #define GATE_LOAD(j) do { pg = *(const float2*)(scr + (j) * 384 + 2 * lane); pa = *(const float2*)(scr + (j) * 384 + 128 + 2 * lane); \
;         ppm = *(const float2*)(scr + (j) * 384 + 256 + 2 * lane); pG = scr[32 * 384 + (j)]; pPM = scr[32 * 384 + 32 + (j)]; } while (0)
; template <int SPLIT> __device__ __forceinline__ void scan_item(const Params& p, unsigned char* smem, const int item, const int vh) {
;     ...
;         for (int j = 0; j < nc; ++j) {
;             const int jn = (j + 1 < nc) ? j + 1 : j;
;             if (wid == 0) {
;                 const float M127 = fmaxf(m_run, pPM);
;                 g_s[2 * lane] = pg.x; g_s[2 * lane + 1] = pg.y; a_s[2 * lane] = pa.x; a_s[2 * lane + 1] = pa.y;
;                 M_s[2 * lane] = fmaxf(m_run, ppm.x); M_s[2 * lane + 1] = fmaxf(m_run, ppm.y);
;                 if (lane == 0) { sc[0] = m_run; sc[1] = M127; }
;                 m_run = pG + M127;
;                 GATE_LOAD(jn);
;             }
.LBB0_290:
	s_sleep 127
	s_add_i32 s0, s95, 17
	s_cmp_lg_u32 s95, -1
	v_readlane_b32 s4, v254, 54
	s_cselect_b32 vcc_lo, s0, 15
	v_readlane_b32 s5, v254, 55
	s_and_saveexec_b64 s[86:87], s[4:5]
	s_cbranch_execz .LBB0_294
	s_waitcnt vmcnt(20)
	v_max_f32_e32 v80, v111, v111
	s_waitcnt lgkmcnt(6)
	v_max_f32_e32 v81, v110, v110
	v_max_f32_e32 v111, v81, v80
	v_max_f32_e32 v80, v98, v98
	v_max_f32_e32 v82, v99, v99
	v_max_f32_e32 v80, v81, v80
	v_max_f32_e32 v81, v81, v82
	ds_write_b64 v117, v[100:101]
	ds_write_b64 v118, v[102:103]
	ds_write_b64 v119, v[80:81]
	s_mov_b64 s[96:97], exec
	v_readlane_b32 s4, v254, 56
	v_readlane_b32 s5, v254, 57
	s_and_b64 s[4:5], s[96:97], s[4:5]
	s_mov_b64 exec, s[4:5]
	v_mov_b32_e32 v80, s94
	ds_write_b64 v80, v[110:111]
	s_or_b64 exec, exec, s[96:97]
	s_mov_b32 vcc_hi, s1
	s_mul_i32 s0, vcc_lo, 0x180
	s_lshl_b64 s[4:5], vcc, 2
	v_lshl_add_u64 v[80:81], s[0:1], 2, v[96:97]
	s_add_u32 s4, s84, s4
	v_add_f32_e32 v110, v115, v111
	s_addc_u32 s5, s85, s5
	global_load_dwordx2 v[100:101], v[80:81], off
	global_load_dwordx2 v[102:103], v[80:81], off offset:512
	global_load_dwordx2 v[98:99], v[80:81], off offset:1024
	global_load_dword v115, v153, s[4:5]
	global_load_dword v111, v153, s[4:5] offset:128
